# GC weight prep moved from the M1 queue tail to the FFN1-up tail of the 128 workgroups with one tile fewer
# speedup vs baseline: 1.0006x; 1.0006x over previous
.LBB0_240:
	s_waitcnt vmcnt(0)
	s_barrier
	s_cmpk_lt_u32 s2, 0x80
	s_cbranch_scc1 .Lpe1_done
	v_writelane_b32 v237, s0, 0
	v_writelane_b32 v237, s1, 1
	v_writelane_b32 v237, s2, 2
	v_writelane_b32 v237, s3, 3
	v_writelane_b32 v237, s4, 4
	v_writelane_b32 v237, s5, 5
	v_writelane_b32 v237, s6, 6
	v_writelane_b32 v237, s7, 7
	v_writelane_b32 v237, s8, 8
	v_writelane_b32 v237, s9, 9
	v_writelane_b32 v237, s10, 10
	v_writelane_b32 v237, s11, 11
	v_writelane_b32 v237, s12, 12
	v_writelane_b32 v237, s13, 13
	v_writelane_b32 v237, s14, 14
	v_writelane_b32 v237, s15, 15
	v_writelane_b32 v237, s16, 16
	v_writelane_b32 v237, s17, 17
	v_writelane_b32 v237, s18, 18
	v_writelane_b32 v237, s19, 19
	v_writelane_b32 v237, s20, 20
	v_writelane_b32 v237, s21, 21
	v_writelane_b32 v237, s22, 22
	v_writelane_b32 v237, s23, 23
	v_writelane_b32 v237, s24, 24
	v_writelane_b32 v237, s25, 25
	v_writelane_b32 v237, s26, 26
	v_writelane_b32 v237, s27, 27
	v_writelane_b32 v237, s28, 28
	v_writelane_b32 v237, s29, 29
	v_writelane_b32 v237, s30, 30
	v_writelane_b32 v237, s31, 31
	v_writelane_b32 v237, s32, 32
	v_writelane_b32 v237, s33, 33
	v_writelane_b32 v237, s34, 34
	v_writelane_b32 v237, s35, 35
	v_writelane_b32 v237, s36, 36
	v_writelane_b32 v237, s37, 37
	v_writelane_b32 v237, s38, 38
	v_writelane_b32 v237, s39, 39
	v_writelane_b32 v237, s40, 40
	v_writelane_b32 v237, s41, 41
	v_writelane_b32 v237, s42, 42
	v_writelane_b32 v237, s43, 43
	v_writelane_b32 v237, s44, 44
	v_writelane_b32 v237, s45, 45
	v_writelane_b32 v237, s46, 46
	v_writelane_b32 v237, s47, 47
	v_writelane_b32 v237, s48, 48
	v_writelane_b32 v237, s49, 49
	v_writelane_b32 v237, s50, 50
	v_writelane_b32 v237, s51, 51
	v_writelane_b32 v237, s52, 52
	v_writelane_b32 v237, s53, 53
	v_writelane_b32 v237, s54, 54
	v_writelane_b32 v237, s55, 55
	v_writelane_b32 v237, s56, 56
	v_writelane_b32 v237, s57, 57
	v_writelane_b32 v237, s58, 58
	v_writelane_b32 v237, s59, 59
	v_writelane_b32 v237, s60, 60
	v_writelane_b32 v237, s61, 61
	v_writelane_b32 v237, s62, 62
	v_writelane_b32 v237, s63, 63
	v_writelane_b32 v238, s64, 0
	v_writelane_b32 v238, s65, 1
	v_writelane_b32 v238, s66, 2
	v_writelane_b32 v238, s67, 3
	v_writelane_b32 v238, s68, 4
	v_writelane_b32 v238, s69, 5
	v_writelane_b32 v238, s70, 6
	v_writelane_b32 v238, s71, 7
	v_writelane_b32 v238, s72, 8
	v_writelane_b32 v238, s73, 9
	v_writelane_b32 v238, s74, 10
	v_writelane_b32 v238, s75, 11
	v_writelane_b32 v238, s76, 12
	v_writelane_b32 v238, s77, 13
	v_writelane_b32 v238, s78, 14
	v_writelane_b32 v238, s79, 15
	v_writelane_b32 v238, s80, 16
	v_writelane_b32 v238, s81, 17
	v_writelane_b32 v238, s82, 18
	v_writelane_b32 v238, s83, 19
	v_writelane_b32 v238, s84, 20
	v_writelane_b32 v238, s85, 21
	v_writelane_b32 v238, s86, 22
	v_writelane_b32 v238, s87, 23
	v_writelane_b32 v238, s88, 24
	v_writelane_b32 v238, s89, 25
	v_writelane_b32 v238, s90, 26
	v_writelane_b32 v238, s91, 27
	v_writelane_b32 v238, s92, 28
	v_writelane_b32 v238, s93, 29
	v_writelane_b32 v238, s94, 30
	v_writelane_b32 v238, s95, 31
	v_writelane_b32 v238, s96, 32
	v_writelane_b32 v238, s97, 33
	v_writelane_b32 v238, s98, 34
	v_writelane_b32 v238, s99, 35
	v_mov_b32_e32 v204, v2
	v_mov_b32_e32 v205, v4
	v_mov_b32_e32 v206, v15
	v_mov_b32_e32 v207, v17
	v_mov_b32_e32 v208, v40
	v_mov_b32_e32 v209, v41
	v_mov_b32_e32 v210, v42
	v_mov_b32_e32 v211, v43
	v_mov_b32_e32 v212, v44
	v_mov_b32_e32 v213, v45
	v_mov_b32_e32 v214, v46
	v_mov_b32_e32 v215, v47
	v_mov_b32_e32 v216, v48
	v_mov_b32_e32 v217, v49
	v_mov_b32_e32 v218, v50
	v_mov_b32_e32 v219, v51
	v_mov_b32_e32 v220, v52
	v_mov_b32_e32 v221, v53
	v_mov_b32_e32 v222, v54
	v_mov_b32_e32 v223, v55
	v_mov_b32_e32 v224, v56
	v_mov_b32_e32 v225, v57
	v_mov_b32_e32 v226, v58
	v_mov_b32_e32 v227, v59
	v_mov_b32_e32 v228, v60
	v_mov_b32_e32 v229, v61
	v_mov_b32_e32 v230, v62
	v_mov_b32_e32 v231, v63
	v_mov_b32_e32 v232, v64
	v_mov_b32_e32 v233, v65
	v_mov_b32_e32 v234, v66
	v_mov_b32_e32 v235, v67
	s_add_u32 s4, s66, 0x38f8400
	v_writelane_b32 v236, s4, 6
	s_addc_u32 s4, s67, 0
	v_writelane_b32 v236, s4, 8
	s_lshl_b32 s4, s52, 10
	s_mov_b32 s5, s69
	v_writelane_b32 v236, s4, 9
	s_mul_i32 s16, s52, 0x300
	s_mov_b32 s17, s69
	v_writelane_b32 v236, s5, 10
	s_add_u32 s4, s66, 0x2df8400
	v_writelane_b32 v236, s4, 11
	s_addc_u32 s4, s67, 0
	v_writelane_b32 v236, s4, 13
	s_lshl_b32 s4, s52, 22
	v_writelane_b32 v236, s4, 15
	s_add_u32 s4, s66, 0x2bf8400
	v_writelane_b32 v236, s4, 17
	s_addc_u32 s4, s67, 0
	v_writelane_b32 v236, s4, 19
	s_lshl_b32 s4, s52, 20
	v_writelane_b32 v236, s4, 21
	s_add_u32 s4, s66, 0x2b78400
	v_writelane_b32 v236, s4, 23
	s_addc_u32 s4, s67, 0
	v_writelane_b32 v236, s4, 25
	s_add_u32 s4, s66, 0x29f8400
	v_writelane_b32 v236, s4, 27
	s_addc_u32 s4, s67, 0
	v_writelane_b32 v236, s4, 28
	s_add_u32 s4, s66, 0x2878400
	v_writelane_b32 v236, s4, 30
	s_addc_u32 s4, s67, 0
	s_add_u32 s14, s66, 0xea78400
	s_addc_u32 s15, s67, 0
	v_writelane_b32 v236, s4, 31
	s_add_u32 s4, s66, 0x2608400
	v_writelane_b32 v236, s4, 32
	s_addc_u32 s4, s67, 0
	v_writelane_b32 v236, s4, 33
	s_add_u32 s4, s66, 0x1c8400
	s_addc_u32 s5, s67, 0
	v_writelane_b32 v236, s4, 34
	s_nop 1
	v_writelane_b32 v236, s5, 35
	s_add_u32 s4, s66, 0x288400
	s_addc_u32 s5, s67, 0
	v_writelane_b32 v236, s4, 36
	s_nop 1
	v_writelane_b32 v236, s5, 37
	s_add_u32 s4, s66, 0x7678400
	s_addc_u32 s5, s67, 0
	v_writelane_b32 v236, s4, 38
	s_nop 1
	v_writelane_b32 v236, s5, 39
	s_add_u32 s4, s66, 0x8e78400
	s_addc_u32 s5, s67, 0
	s_add_u32 s61, s66, 0x408400
	s_addc_u32 s78, s67, 0
	s_add_u32 s79, s66, 0x100400
	v_writelane_b32 v236, s4, 40
	s_addc_u32 s86, s67, 0
	s_nop 0
	v_writelane_b32 v236, s5, 41
	s_add_u32 s4, s66, 0x3a8400
	v_writelane_b32 v236, s4, 42
	s_addc_u32 s4, s67, 0
	s_add_u32 s89, s66, 0x348400
	s_addc_u32 s90, s67, 0
	v_writelane_b32 v236, s4, 43
	s_add_i32 s91, s2, 0x740
.Lpe1_loop:
	s_mov_b64 s[10:11], -1
	v_mov_b32_e32 v8, v203
	s_lshl_b32 s5, s91, 3
	v_readfirstlane_b32 s4, v8
	s_ashr_i32 s4, s4, 6
	s_add_i32 s31, s5, s4
	s_addk_i32 s31, 0xc200
	s_cmpk_gt_i32 s31, 0x15ff
	s_cbranch_scc1 .Lpe1_next
	s_mulk_i32 s4, 0x2100
	s_add_i32 s30, s4, 0
	v_and_b32_e32 v10, 63, v8
	s_cmpk_gt_i32 s31, 0x17f
	s_cbranch_scc0 .LBB0_616
	s_cmpk_gt_u32 s31, 0x2ff
	s_cbranch_scc0 .LBB0_613
	s_cmpk_gt_u32 s31, 0x37f
	s_cbranch_scc0 .LBB0_610
	s_cmpk_gt_u32 s31, 0x57f
	s_cbranch_scc0 .LBB0_607
	s_cmpk_gt_u32 s31, 0xaff
	s_cbranch_scc0 .LBB0_588
	s_cmpk_gt_u32 s31, 0x107f
	s_cbranch_scc0 .LBB0_569
	s_movk_i32 s4, 0xd8
	v_readlane_b32 s10, v250, 57
	v_readlane_b32 s11, v250, 58
	s_load_dwordx2 s[4:5], s[10:11], s4 offset:0x0
	s_mul_i32 s10, s52, 0xb00000
	v_and_b32_e32 v3, 7, v8
	v_lshlrev_b32_e32 v2, 4, v3
	v_lshrrev_b32_e32 v9, 3, v10
	s_waitcnt lgkmcnt(0)
	s_add_u32 s10, s4, s10
	s_addc_u32 s11, s5, 0
	s_lshl_b32 s4, s31, 1
	s_add_i32 s4, s4, 0x1df00
	s_and_b32 s5, s4, 0x1ffc0
	s_lshl_b32 s4, s31, 5
	s_and_b32 s4, s4, 0x3e0
	v_lshl_or_b32 v0, s4, 2, v2
	v_lshl_add_u64 v[12:13], s[10:11], 0, v[0:1]
	v_or_b32_e32 v0, s5, v9
	v_lshlrev_b32_e32 v0, 12, v0
	v_lshl_add_u64 v[4:5], v[12:13], 0, v[0:1]
	v_mov_b32_e32 v68, 0x8000
	v_mov_b32_e32 v69, 0
	v_lshl_add_u64 v[70:71], v[4:5], 0, v[68:69]
	global_load_dwordx4 v[40:43], v[70:71], off
	v_lshl_add_u64 v[70:71], v[70:71], 0, v[68:69]
	global_load_dwordx4 v[44:47], v[70:71], off
	v_lshl_add_u64 v[70:71], v[70:71], 0, v[68:69]
	global_load_dwordx4 v[48:51], v[70:71], off
	v_lshl_add_u64 v[70:71], v[70:71], 0, v[68:69]
	global_load_dwordx4 v[52:55], v[70:71], off
	v_lshl_add_u64 v[70:71], v[70:71], 0, v[68:69]
	global_load_dwordx4 v[56:59], v[70:71], off
	v_lshl_add_u64 v[70:71], v[70:71], 0, v[68:69]
	global_load_dwordx4 v[60:63], v[70:71], off
	v_lshl_add_u64 v[70:71], v[70:71], 0, v[68:69]
	global_load_dwordx4 v[64:67], v[70:71], off
	global_load_dwordx4 v[4:7], v[4:5], off
	v_mul_u32_u24_e32 v11, 0x84, v9
	v_add3_u32 v11, s30, v2, v11
	v_or_b32_e32 v30, 8, v9
	v_add_u32_e32 v14, 0x420, v11
	v_or_b32_e32 v31, 16, v9
	v_or_b32_e32 v32, 24, v9
	v_readlane_b32 s10, v236, 6
	s_waitcnt vmcnt(0)
	ds_write2_b32 v11, v4, v5 offset1:1
	ds_write2_b32 v11, v6, v7 offset0:2 offset1:3
	v_or_b32_e32 v4, s5, v30
	v_lshlrev_b32_e32 v4, 12, v4
	v_mov_b32_e32 v5, v1
	v_lshl_add_u64 v[4:5], v[12:13], 0, v[4:5]
	v_mov_b64_e32 v[4:5], v[40:41]
	v_mov_b64_e32 v[6:7], v[42:43]
	s_waitcnt vmcnt(0)
	ds_write2_b32 v14, v4, v5 offset1:1
	v_add_u32_e32 v4, 0x428, v11
	ds_write2_b32 v4, v6, v7 offset1:1
	v_or_b32_e32 v4, s5, v31
	v_lshlrev_b32_e32 v4, 12, v4
	v_mov_b32_e32 v5, v1
	v_lshl_add_u64 v[4:5], v[12:13], 0, v[4:5]
	v_mov_b64_e32 v[4:5], v[44:45]
	v_mov_b64_e32 v[6:7], v[46:47]
	v_add_u32_e32 v14, 0x840, v11
	s_waitcnt vmcnt(0)
	ds_write2_b32 v14, v4, v5 offset1:1
	v_add_u32_e32 v4, 0x848, v11
	ds_write2_b32 v4, v6, v7 offset1:1
	v_or_b32_e32 v4, s5, v32
	v_lshlrev_b32_e32 v4, 12, v4
	v_mov_b32_e32 v5, v1
	v_lshl_add_u64 v[4:5], v[12:13], 0, v[4:5]
	v_mov_b64_e32 v[4:5], v[48:49]
	v_mov_b64_e32 v[6:7], v[50:51]
	v_add_u32_e32 v14, 0xc60, v11
	s_lshl_b32 s5, s5, 1
	s_add_u32 s10, s10, s5
	v_readlane_b32 s5, v236, 8
	s_addc_u32 s11, s5, 0
	s_waitcnt vmcnt(0)
	ds_write2_b32 v14, v4, v5 offset1:1
	v_add_u32_e32 v4, 0xc68, v11
	ds_write2_b32 v4, v6, v7 offset1:1
	v_or_b32_e32 v4, 0x20000, v0
	v_mov_b32_e32 v5, v1
	v_lshl_add_u64 v[4:5], v[12:13], 0, v[4:5]
	v_mov_b64_e32 v[4:5], v[52:53]
	v_mov_b64_e32 v[6:7], v[54:55]
	v_add_u32_e32 v14, 0x1080, v11
	s_waitcnt vmcnt(0)
	ds_write2_b32 v14, v4, v5 offset1:1
	v_add_u32_e32 v4, 0x1088, v11
	ds_write2_b32 v4, v6, v7 offset1:1
	v_or_b32_e32 v4, 0x28000, v0
	v_mov_b32_e32 v5, v1
	v_lshl_add_u64 v[4:5], v[12:13], 0, v[4:5]
	v_mov_b64_e32 v[4:5], v[56:57]
	v_mov_b64_e32 v[6:7], v[58:59]
	v_add_u32_e32 v14, 0x14a0, v11
	s_waitcnt vmcnt(0)
	ds_write2_b32 v14, v4, v5 offset1:1
	v_add_u32_e32 v4, 0x14a8, v11
	ds_write2_b32 v4, v6, v7 offset1:1
	v_or_b32_e32 v4, 0x30000, v0
	v_mov_b32_e32 v5, v1
	v_lshl_add_u64 v[4:5], v[12:13], 0, v[4:5]
	v_mov_b64_e32 v[4:5], v[60:61]
	v_mov_b64_e32 v[6:7], v[62:63]
	v_add_u32_e32 v14, 0x18c0, v11
	v_or_b32_e32 v0, 0x38000, v0
	s_waitcnt vmcnt(0)
	ds_write2_b32 v14, v4, v5 offset1:1
	v_add_u32_e32 v4, 0x18c8, v11
	ds_write2_b32 v4, v6, v7 offset1:1
	v_lshl_add_u64 v[4:5], v[12:13], 0, v[0:1]
	v_mov_b64_e32 v[4:5], v[64:65]
	v_mov_b64_e32 v[6:7], v[66:67]
	v_add_u32_e32 v0, 0x1ce0, v11
	s_waitcnt vmcnt(0)
	ds_write2_b32 v0, v4, v5 offset1:1
	v_add_u32_e32 v0, 0x1ce8, v11
	ds_write2_b32 v0, v6, v7 offset1:1
	v_mul_u32_u24_e32 v0, 0x420, v3
	v_lshlrev_b32_e32 v4, 2, v9
	s_waitcnt lgkmcnt(0)
	v_or_b32_e32 v11, s4, v9
	v_add3_u32 v9, s30, v0, v4
	ds_read2_b32 v[12:13], v9 offset0:198 offset1:206
	ds_read2_b32 v[14:15], v9 offset0:231 offset1:239
	ds_read2_b32 v[16:17], v9 offset0:132 offset1:140
	ds_read2_b32 v[18:19], v9 offset0:165 offset1:173
	ds_read2_b32 v[20:21], v9 offset0:66 offset1:74
	ds_read2_b32 v[22:23], v9 offset0:99 offset1:107
	ds_read2_b32 v[24:25], v9 offset0:33 offset1:41
	ds_read2_b32 v[26:27], v9 offset1:8
	v_mov_b32_e32 v3, v1
	v_mul_u32_u24_e32 v0, 0xb00, v11
	v_lshl_add_u64 v[2:3], s[10:11], 0, v[2:3]
	v_lshlrev_b32_e32 v0, 1, v0
	v_lshl_add_u64 v[28:29], v[2:3], 0, v[0:1]
	v_or_b32_e32 v0, s4, v30
	v_mul_u32_u24_e32 v0, 0xb00, v0
	s_waitcnt lgkmcnt(6)
	v_cvt_pk_bf16_f32 v7, v12, v14
	s_waitcnt lgkmcnt(4)
	v_cvt_pk_bf16_f32 v6, v16, v18
	s_waitcnt lgkmcnt(2)
	v_cvt_pk_bf16_f32 v5, v20, v22
	s_waitcnt lgkmcnt(0)
	v_cvt_pk_bf16_f32 v4, v26, v24
	v_lshlrev_b32_e32 v0, 1, v0
	global_store_dwordx4 v[28:29], v[4:7], off
	s_mov_b64 s[10:11], 0
	s_nop 0
	v_cvt_pk_bf16_f32 v7, v13, v15
	v_cvt_pk_bf16_f32 v6, v17, v19
	v_cvt_pk_bf16_f32 v5, v21, v23
	v_cvt_pk_bf16_f32 v4, v27, v25
	v_lshl_add_u64 v[12:13], v[2:3], 0, v[0:1]
	global_store_dwordx4 v[12:13], v[4:7], off
	v_or_b32_e32 v0, s4, v31
	ds_read2_b32 v[12:13], v9 offset0:214 offset1:222
	ds_read2_b32 v[14:15], v9 offset0:247 offset1:255
	ds_read2_b32 v[16:17], v9 offset0:148 offset1:156
	ds_read2_b32 v[18:19], v9 offset0:181 offset1:189
	ds_read2_b32 v[20:21], v9 offset0:82 offset1:90
	ds_read2_b32 v[22:23], v9 offset0:115 offset1:123
	ds_read2_b32 v[24:25], v9 offset0:16 offset1:24
	ds_read2_b32 v[26:27], v9 offset0:49 offset1:57
	v_mul_u32_u24_e32 v0, 0xb00, v0
	v_lshlrev_b32_e32 v0, 1, v0
	v_lshl_add_u64 v[28:29], v[2:3], 0, v[0:1]
	v_or_b32_e32 v0, s4, v32
	v_mul_u32_u24_e32 v0, 0xb00, v0
	s_waitcnt lgkmcnt(6)
	v_cvt_pk_bf16_f32 v7, v12, v14
	s_waitcnt lgkmcnt(4)
	v_cvt_pk_bf16_f32 v6, v16, v18
	s_waitcnt lgkmcnt(2)
	v_cvt_pk_bf16_f32 v5, v20, v22
	s_waitcnt lgkmcnt(0)
	v_cvt_pk_bf16_f32 v4, v24, v26
	v_lshlrev_b32_e32 v0, 1, v0
	global_store_dwordx4 v[28:29], v[4:7], off
	v_lshl_add_u64 v[2:3], v[2:3], 0, v[0:1]
	s_nop 0
	v_cvt_pk_bf16_f32 v7, v13, v15
	v_cvt_pk_bf16_f32 v6, v17, v19
	v_cvt_pk_bf16_f32 v5, v21, v23
	v_cvt_pk_bf16_f32 v4, v25, v27
	global_store_dwordx4 v[2:3], v[4:7], off
	s_waitcnt lgkmcnt(0)
.LBB0_569:
	s_andn2_b64 vcc, exec, s[10:11]
	s_cbranch_vccnz .LBB0_587
	s_movk_i32 s4, 0xd0
	v_readlane_b32 s12, v250, 57
	v_readlane_b32 s13, v250, 58
	s_load_dwordx2 s[4:5], s[12:13], s4 offset:0x0
	s_movk_i32 s10, 0xc0
	s_load_dwordx2 s[10:11], s[12:13], s10 offset:0x0
	s_mul_i32 s12, s52, 0xb00000
	s_waitcnt lgkmcnt(0)
	s_add_u32 s12, s4, s12
	s_addc_u32 s13, s5, 0
	v_readlane_b32 s4, v236, 9
	v_readlane_b32 s5, v236, 10
	s_lshl_b64 s[4:5], s[4:5], 2
	s_add_u32 s26, s10, s4
	s_addc_u32 s27, s11, s5
	s_add_i32 s4, s31, 0xf500
	s_and_b32 s5, s4, 0xffff
	s_mul_i32 s5, s5, 0xba2f
	s_lshr_b32 s18, s5, 16
	s_lshr_b32 s5, s5, 22
	s_mulk_i32 s5, 0x58
	s_sub_i32 s4, s4, s5
	s_lshl_b32 s4, s4, 5
	v_and_b32_e32 v12, 7, v8
	s_and_b32 s4, s4, 0xffe0
	v_lshlrev_b32_e32 v11, 2, v12
	s_and_b32 s5, s18, 0xffc0
	v_or_b32_e32 v0, s4, v11
	v_lshrrev_b32_e32 v9, 3, v10
	v_lshlrev_b32_e32 v0, 2, v0
	v_or_b32_e32 v13, s5, v9
	v_lshl_add_u64 v[6:7], s[12:13], 0, v[0:1]
	v_mul_u32_u24_e32 v0, 0xb00, v13
	v_lshlrev_b32_e32 v0, 2, v0
	v_lshl_add_u64 v[2:3], v[6:7], 0, v[0:1]
	v_mov_b32_e32 v68, 0x16000
	v_mov_b32_e32 v69, 0
	v_lshl_add_u64 v[70:71], v[2:3], 0, v[68:69]
	global_load_dwordx4 v[40:43], v[70:71], off
	v_lshl_add_u64 v[70:71], v[70:71], 0, v[68:69]
	global_load_dwordx4 v[44:47], v[70:71], off
	v_lshl_add_u64 v[70:71], v[70:71], 0, v[68:69]
	global_load_dwordx4 v[48:51], v[70:71], off
	v_lshl_add_u64 v[70:71], v[70:71], 0, v[68:69]
	global_load_dwordx4 v[52:55], v[70:71], off
	v_lshl_add_u64 v[70:71], v[70:71], 0, v[68:69]
	global_load_dwordx4 v[56:59], v[70:71], off
	v_lshl_add_u64 v[70:71], v[70:71], 0, v[68:69]
	global_load_dwordx4 v[60:63], v[70:71], off
	v_lshl_add_u64 v[70:71], v[70:71], 0, v[68:69]
	global_load_dwordx4 v[64:67], v[70:71], off
	global_load_dwordx4 v[2:5], v[2:3], off
	s_cmp_lg_u64 s[10:11], 0
	s_cselect_b64 s[28:29], -1, 0
	s_cmp_eq_u64 s[10:11], 0
	s_cbranch_scc1 .LBB0_572
	v_lshlrev_b32_e32 v0, 2, v13
	global_load_dword v72, v0, s[26:27] offset:128
	global_load_dword v0, v0, s[26:27]
	s_waitcnt vmcnt(0)
	v_pk_mul_f32 v[4:5], v[4:5], v[0:1] op_sel_hi:[1,0]
	v_pk_mul_f32 v[2:3], v[2:3], v[0:1] op_sel_hi:[1,0]

.LBB0_586:
	v_add_u32_e32 v0, 0x1ce0, v16
	s_lshl_b32 s5, s5, 1
	v_readlane_b32 s10, v236, 11
	s_waitcnt vmcnt(0)
	ds_write2_b32 v0, v2, v3 offset1:1
	v_add_u32_e32 v0, 0x1ce8, v16
	s_add_u32 s10, s10, s5
	v_readlane_b32 s5, v236, 13
	ds_write2_b32 v0, v4, v5 offset1:1
	s_addc_u32 s11, s5, 0
	v_lshlrev_b32_e32 v0, 4, v12
	v_mul_u32_u24_e32 v2, 0x420, v12
	v_lshl_add_u64 v[6:7], s[10:11], 0, v[0:1]
	v_lshlrev_b32_e32 v0, 2, v9
	v_add3_u32 v12, s30, v2, v0
	v_or_b32_e32 v0, s4, v9
	s_waitcnt lgkmcnt(0)
	v_lshlrev_b32_e32 v0, 1, v0
	s_movk_i32 s5, 0x1fc8
	ds_read2_b32 v[16:17], v12 offset0:33 offset1:41
	ds_read2_b32 v[18:19], v12 offset1:8
	ds_read2_b32 v[20:21], v12 offset0:66 offset1:74
	ds_read2_b32 v[22:23], v12 offset0:99 offset1:107
	ds_read2_b32 v[24:25], v12 offset0:132 offset1:140
	ds_read2_b32 v[26:27], v12 offset0:165 offset1:173
	ds_read2_b32 v[28:29], v12 offset0:198 offset1:206
	ds_read2_b32 v[30:31], v12 offset0:231 offset1:239
	v_and_or_b32 v0, v0, s5, v9
	v_lshl_or_b32 v0, v0, 11, v192
	v_lshl_add_u64 v[32:33], v[6:7], 0, v[0:1]
	v_or_b32_e32 v0, s4, v11
	v_lshlrev_b32_e32 v0, 1, v0
	s_movk_i32 s5, 0x1fd8
	v_and_or_b32 v0, v0, s5, v9
	s_waitcnt lgkmcnt(6)
	v_cvt_pk_bf16_f32 v2, v18, v16
	s_waitcnt lgkmcnt(4)
	v_cvt_pk_bf16_f32 v3, v20, v22
	s_waitcnt lgkmcnt(2)
	v_cvt_pk_bf16_f32 v4, v24, v26
	s_waitcnt lgkmcnt(0)
	v_cvt_pk_bf16_f32 v5, v28, v30
	v_lshl_or_b32 v0, v0, 11, v192
	global_store_dwordx4 v[32:33], v[2:5], off
	s_movk_i32 s5, 0x1fe8
	s_nop 0
	v_cvt_pk_bf16_f32 v2, v19, v17
	v_cvt_pk_bf16_f32 v3, v21, v23
	v_cvt_pk_bf16_f32 v4, v25, v27
	v_cvt_pk_bf16_f32 v5, v29, v31
	v_lshl_add_u64 v[16:17], v[6:7], 0, v[0:1]
	v_or_b32_e32 v0, s4, v13
	global_store_dwordx4 v[16:17], v[2:5], off
	v_lshlrev_b32_e32 v0, 1, v0
	ds_read2_b32 v[16:17], v12 offset0:16 offset1:24
	ds_read2_b32 v[18:19], v12 offset0:49 offset1:57
	ds_read2_b32 v[20:21], v12 offset0:82 offset1:90
	ds_read2_b32 v[22:23], v12 offset0:115 offset1:123
	ds_read2_b32 v[24:25], v12 offset0:148 offset1:156
	ds_read2_b32 v[26:27], v12 offset0:181 offset1:189
	ds_read2_b32 v[28:29], v12 offset0:214 offset1:222
	ds_read2_b32 v[30:31], v12 offset0:247 offset1:255
	v_and_or_b32 v0, v0, s5, v9
	v_lshl_or_b32 v0, v0, 11, v192
	v_lshl_add_u64 v[12:13], v[6:7], 0, v[0:1]
	v_or_b32_e32 v0, s4, v14
	v_lshlrev_b32_e32 v0, 1, v0
	s_movk_i32 s4, 0x1ff8
	v_and_or_b32 v0, v0, s4, v9
	s_waitcnt lgkmcnt(6)
	v_cvt_pk_bf16_f32 v2, v16, v18
	s_waitcnt lgkmcnt(4)
	v_cvt_pk_bf16_f32 v3, v20, v22
	s_waitcnt lgkmcnt(2)
	v_cvt_pk_bf16_f32 v4, v24, v26
	s_waitcnt lgkmcnt(0)
	v_cvt_pk_bf16_f32 v5, v28, v30
	v_lshl_or_b32 v0, v0, 11, v192
	global_store_dwordx4 v[12:13], v[2:5], off
	v_lshl_add_u64 v[6:7], v[6:7], 0, v[0:1]
	s_nop 0
	v_cvt_pk_bf16_f32 v2, v17, v19
	v_cvt_pk_bf16_f32 v3, v21, v23
	v_cvt_pk_bf16_f32 v4, v25, v27
	v_cvt_pk_bf16_f32 v5, v29, v31
	global_store_dwordx4 v[6:7], v[2:5], off
	s_waitcnt lgkmcnt(0)

.LBB0_588:
	s_andn2_b64 vcc, exec, s[10:11]
	s_cbranch_vccnz .LBB0_606
	s_movk_i32 s4, 0xc8
	v_readlane_b32 s12, v250, 57
	v_readlane_b32 s13, v250, 58
	s_load_dwordx2 s[4:5], s[12:13], s4 offset:0x0
	s_movk_i32 s10, 0xc0
	s_load_dwordx2 s[10:11], s[12:13], s10 offset:0x0
	s_mul_i32 s12, s52, 0xb00000
	s_waitcnt lgkmcnt(0)
	s_add_u32 s12, s4, s12
	s_addc_u32 s13, s5, 0
	v_readlane_b32 s4, v236, 9
	v_readlane_b32 s5, v236, 10
	s_lshl_b64 s[4:5], s[4:5], 2
	s_add_u32 s26, s10, s4
	s_addc_u32 s27, s11, s5
	s_add_i32 s4, s31, 0xfa80
	s_and_b32 s5, s4, 0xffff
	s_mul_i32 s5, s5, 0xba2f
	s_lshr_b32 s18, s5, 16
	s_lshr_b32 s5, s5, 22
	s_mulk_i32 s5, 0x58
	s_sub_i32 s4, s4, s5
	s_lshl_b32 s4, s4, 5
	v_and_b32_e32 v12, 7, v8
	s_and_b32 s4, s4, 0xffe0
	v_lshlrev_b32_e32 v11, 2, v12
	v_or_b32_e32 v0, s4, v11
	s_and_b32 s5, s18, 0xffc0
	v_lshlrev_b32_e32 v0, 2, v0
	v_lshrrev_b32_e32 v9, 3, v10
	v_lshl_add_u64 v[6:7], s[12:13], 0, v[0:1]
	v_or_b32_e32 v0, s5, v9
	s_movk_i32 s12, 0x2c00
	v_mad_u64_u32 v[2:3], s[12:13], v0, s12, v[6:7]
	v_mov_b32_e32 v68, 0x16000
	v_mov_b32_e32 v69, 0
	v_lshl_add_u64 v[70:71], v[2:3], 0, v[68:69]
	global_load_dwordx4 v[40:43], v[70:71], off
	v_lshl_add_u64 v[70:71], v[70:71], 0, v[68:69]
	global_load_dwordx4 v[44:47], v[70:71], off
	v_lshl_add_u64 v[70:71], v[70:71], 0, v[68:69]
	global_load_dwordx4 v[48:51], v[70:71], off
	v_lshl_add_u64 v[70:71], v[70:71], 0, v[68:69]
	global_load_dwordx4 v[52:55], v[70:71], off
	v_lshl_add_u64 v[70:71], v[70:71], 0, v[68:69]
	global_load_dwordx4 v[56:59], v[70:71], off
	v_lshl_add_u64 v[70:71], v[70:71], 0, v[68:69]
	global_load_dwordx4 v[60:63], v[70:71], off
	v_lshl_add_u64 v[70:71], v[70:71], 0, v[68:69]
	global_load_dwordx4 v[64:67], v[70:71], off
	global_load_dwordx4 v[2:5], v[2:3], off
	s_cmp_lg_u64 s[10:11], 0
	s_cselect_b64 s[28:29], -1, 0
	s_cmp_eq_u64 s[10:11], 0
	s_cbranch_scc1 .LBB0_591
	v_lshlrev_b32_e32 v0, 2, v0
	global_load_dword v72, v0, s[26:27] offset:128
	global_load_dword v0, v0, s[26:27]
	s_waitcnt vmcnt(0)
	v_pk_mul_f32 v[4:5], v[4:5], v[0:1] op_sel_hi:[1,0]
	v_pk_mul_f32 v[2:3], v[2:3], v[0:1] op_sel_hi:[1,0]

.LBB0_605:
	v_add_u32_e32 v0, 0x1ce0, v15
	s_lshl_b32 s5, s5, 1
	v_readlane_b32 s10, v236, 11
	s_waitcnt vmcnt(0)
	ds_write2_b32 v0, v2, v3 offset1:1
	v_add_u32_e32 v0, 0x1ce8, v15
	s_add_u32 s10, s10, s5
	v_readlane_b32 s5, v236, 13
	ds_write2_b32 v0, v4, v5 offset1:1
	s_addc_u32 s11, s5, 0
	v_lshlrev_b32_e32 v0, 4, v12
	v_mul_u32_u24_e32 v2, 0x420, v12
	v_lshl_add_u64 v[6:7], s[10:11], 0, v[0:1]
	v_lshlrev_b32_e32 v0, 2, v9
	v_add3_u32 v12, s30, v2, v0
	v_or_b32_e32 v0, s4, v9
	s_waitcnt lgkmcnt(0)
	v_bfe_u32 v15, v10, 3, 2
	v_lshlrev_b32_e32 v0, 1, v0
	s_movk_i32 s5, 0x1fc8
	ds_read2_b32 v[16:17], v12 offset0:33 offset1:41
	ds_read2_b32 v[18:19], v12 offset1:8
	ds_read2_b32 v[20:21], v12 offset0:66 offset1:74
	ds_read2_b32 v[22:23], v12 offset0:99 offset1:107
	ds_read2_b32 v[24:25], v12 offset0:132 offset1:140
	ds_read2_b32 v[26:27], v12 offset0:165 offset1:173
	ds_read2_b32 v[28:29], v12 offset0:198 offset1:206
	ds_read2_b32 v[30:31], v12 offset0:231 offset1:239
	v_and_or_b32 v0, v0, s5, v15
	v_lshlrev_b32_e32 v0, 11, v0
	v_lshl_add_u64 v[32:33], v[6:7], 0, v[0:1]
	v_or_b32_e32 v0, s4, v11
	v_lshlrev_b32_e32 v0, 1, v0
	s_movk_i32 s5, 0x1fd8
	v_and_or_b32 v0, v0, s5, v15
	s_waitcnt lgkmcnt(6)
	v_cvt_pk_bf16_f32 v2, v18, v16
	s_waitcnt lgkmcnt(4)
	v_cvt_pk_bf16_f32 v3, v20, v22
	s_waitcnt lgkmcnt(2)
	v_cvt_pk_bf16_f32 v4, v24, v26
	s_waitcnt lgkmcnt(0)
	v_cvt_pk_bf16_f32 v5, v28, v30
	v_lshlrev_b32_e32 v0, 11, v0
	global_store_dwordx4 v[32:33], v[2:5], off
	s_movk_i32 s5, 0x1fe8
	s_nop 0
	v_cvt_pk_bf16_f32 v2, v19, v17
	v_cvt_pk_bf16_f32 v3, v21, v23
	v_cvt_pk_bf16_f32 v4, v25, v27
	v_cvt_pk_bf16_f32 v5, v29, v31
	v_lshl_add_u64 v[16:17], v[6:7], 0, v[0:1]
	v_or_b32_e32 v0, s4, v13
	global_store_dwordx4 v[16:17], v[2:5], off
	v_lshlrev_b32_e32 v0, 1, v0
	ds_read2_b32 v[16:17], v12 offset0:49 offset1:57
	ds_read2_b32 v[18:19], v12 offset0:16 offset1:24
	ds_read2_b32 v[20:21], v12 offset0:82 offset1:90
	ds_read2_b32 v[22:23], v12 offset0:115 offset1:123
	ds_read2_b32 v[24:25], v12 offset0:148 offset1:156
	ds_read2_b32 v[26:27], v12 offset0:181 offset1:189
	ds_read2_b32 v[28:29], v12 offset0:214 offset1:222
	ds_read2_b32 v[30:31], v12 offset0:247 offset1:255
	v_and_or_b32 v0, v0, s5, v15
	v_lshlrev_b32_e32 v0, 11, v0
	v_lshl_add_u64 v[12:13], v[6:7], 0, v[0:1]
	v_or_b32_e32 v0, s4, v14
	v_lshlrev_b32_e32 v0, 1, v0
	s_movk_i32 s4, 0x1ff8
	v_and_or_b32 v0, v0, s4, v15
	s_waitcnt lgkmcnt(6)
	v_cvt_pk_bf16_f32 v2, v18, v16
	s_waitcnt lgkmcnt(4)
	v_cvt_pk_bf16_f32 v3, v20, v22
	s_waitcnt lgkmcnt(2)
	v_cvt_pk_bf16_f32 v4, v24, v26
	s_waitcnt lgkmcnt(0)
	v_cvt_pk_bf16_f32 v5, v28, v30
	v_lshlrev_b32_e32 v0, 11, v0
	global_store_dwordx4 v[12:13], v[2:5], off
	v_lshl_add_u64 v[6:7], v[6:7], 0, v[0:1]
	s_nop 0
	v_cvt_pk_bf16_f32 v2, v19, v17
	v_cvt_pk_bf16_f32 v3, v21, v23
	v_cvt_pk_bf16_f32 v4, v25, v27
	v_cvt_pk_bf16_f32 v5, v29, v31
	global_store_dwordx4 v[6:7], v[2:5], off
	s_waitcnt lgkmcnt(0)

.LBB0_607:
	s_andn2_b64 vcc, exec, s[10:11]
	s_cbranch_vccnz .LBB0_609
	s_movk_i32 s4, 0xb8
	v_readlane_b32 s10, v250, 57
	v_readlane_b32 s11, v250, 58
	s_load_dwordx2 s[4:5], s[10:11], s4 offset:0x0
	v_readlane_b32 s10, v236, 15
	v_and_b32_e32 v3, 7, v8
	v_lshlrev_b32_e32 v2, 4, v3
	v_lshrrev_b32_e32 v9, 3, v10
	s_waitcnt lgkmcnt(0)
	s_add_u32 s10, s4, s10
	s_addc_u32 s11, s5, 0
	s_lshl_b32 s4, s31, 1
	s_add_i32 s4, s4, 0x1f900
	s_and_b32 s5, s4, 0x1ffc0
	s_lshl_b32 s4, s31, 5
	s_and_b32 s4, s4, 0x3e0
	v_lshl_or_b32 v0, s4, 2, v2
	v_lshl_add_u64 v[12:13], s[10:11], 0, v[0:1]
	v_or_b32_e32 v0, s5, v9
	v_lshlrev_b32_e32 v0, 12, v0
	v_lshl_add_u64 v[4:5], v[12:13], 0, v[0:1]
	v_mov_b32_e32 v68, 0x8000
	v_mov_b32_e32 v69, 0
	v_lshl_add_u64 v[70:71], v[4:5], 0, v[68:69]
	global_load_dwordx4 v[40:43], v[70:71], off
	v_lshl_add_u64 v[70:71], v[70:71], 0, v[68:69]
	global_load_dwordx4 v[44:47], v[70:71], off
	v_lshl_add_u64 v[70:71], v[70:71], 0, v[68:69]
	global_load_dwordx4 v[48:51], v[70:71], off
	v_lshl_add_u64 v[70:71], v[70:71], 0, v[68:69]
	global_load_dwordx4 v[52:55], v[70:71], off
	v_lshl_add_u64 v[70:71], v[70:71], 0, v[68:69]
	global_load_dwordx4 v[56:59], v[70:71], off
	v_lshl_add_u64 v[70:71], v[70:71], 0, v[68:69]
	global_load_dwordx4 v[60:63], v[70:71], off
	v_lshl_add_u64 v[70:71], v[70:71], 0, v[68:69]
	global_load_dwordx4 v[64:67], v[70:71], off
	global_load_dwordx4 v[4:7], v[4:5], off
	v_mul_u32_u24_e32 v11, 0x84, v9
	v_add3_u32 v11, s30, v2, v11
	v_or_b32_e32 v30, 8, v9
	v_add_u32_e32 v14, 0x420, v11
	v_or_b32_e32 v31, 16, v9
	v_or_b32_e32 v32, 24, v9
	v_readlane_b32 s10, v236, 17
	s_waitcnt vmcnt(0)
	ds_write2_b32 v11, v4, v5 offset1:1
	ds_write2_b32 v11, v6, v7 offset0:2 offset1:3
	v_or_b32_e32 v4, s5, v30
	v_lshlrev_b32_e32 v4, 12, v4
	v_mov_b32_e32 v5, v1
	v_lshl_add_u64 v[4:5], v[12:13], 0, v[4:5]
	v_mov_b64_e32 v[4:5], v[40:41]
	v_mov_b64_e32 v[6:7], v[42:43]
	s_waitcnt vmcnt(0)
	ds_write2_b32 v14, v4, v5 offset1:1
	v_add_u32_e32 v4, 0x428, v11
	ds_write2_b32 v4, v6, v7 offset1:1
	v_or_b32_e32 v4, s5, v31
	v_lshlrev_b32_e32 v4, 12, v4
	v_mov_b32_e32 v5, v1
	v_lshl_add_u64 v[4:5], v[12:13], 0, v[4:5]
	v_mov_b64_e32 v[4:5], v[44:45]
	v_mov_b64_e32 v[6:7], v[46:47]
	v_add_u32_e32 v14, 0x840, v11
	s_waitcnt vmcnt(0)
	ds_write2_b32 v14, v4, v5 offset1:1
	v_add_u32_e32 v4, 0x848, v11
	ds_write2_b32 v4, v6, v7 offset1:1
	v_or_b32_e32 v4, s5, v32
	v_lshlrev_b32_e32 v4, 12, v4
	v_mov_b32_e32 v5, v1
	v_lshl_add_u64 v[4:5], v[12:13], 0, v[4:5]
	v_mov_b64_e32 v[4:5], v[48:49]
	v_mov_b64_e32 v[6:7], v[50:51]
	v_add_u32_e32 v14, 0xc60, v11
	s_lshl_b32 s5, s5, 1
	s_add_u32 s10, s10, s5
	v_readlane_b32 s5, v236, 19
	s_addc_u32 s11, s5, 0
	s_waitcnt vmcnt(0)
	ds_write2_b32 v14, v4, v5 offset1:1
	v_add_u32_e32 v4, 0xc68, v11
	ds_write2_b32 v4, v6, v7 offset1:1
	v_or_b32_e32 v4, 0x20000, v0
	v_mov_b32_e32 v5, v1
	v_lshl_add_u64 v[4:5], v[12:13], 0, v[4:5]
	v_mov_b64_e32 v[4:5], v[52:53]
	v_mov_b64_e32 v[6:7], v[54:55]
	v_add_u32_e32 v14, 0x1080, v11
	s_waitcnt vmcnt(0)
	ds_write2_b32 v14, v4, v5 offset1:1
	v_add_u32_e32 v4, 0x1088, v11
	ds_write2_b32 v4, v6, v7 offset1:1
	v_or_b32_e32 v4, 0x28000, v0
	v_mov_b32_e32 v5, v1
	v_lshl_add_u64 v[4:5], v[12:13], 0, v[4:5]
	v_mov_b64_e32 v[4:5], v[56:57]
	v_mov_b64_e32 v[6:7], v[58:59]
	v_add_u32_e32 v14, 0x14a0, v11
	s_waitcnt vmcnt(0)
	ds_write2_b32 v14, v4, v5 offset1:1
	v_add_u32_e32 v4, 0x14a8, v11
	ds_write2_b32 v4, v6, v7 offset1:1
	v_or_b32_e32 v4, 0x30000, v0
	v_mov_b32_e32 v5, v1
	v_lshl_add_u64 v[4:5], v[12:13], 0, v[4:5]
	v_mov_b64_e32 v[4:5], v[60:61]
	v_mov_b64_e32 v[6:7], v[62:63]
	v_add_u32_e32 v14, 0x18c0, v11
	v_or_b32_e32 v0, 0x38000, v0
	s_waitcnt vmcnt(0)
	ds_write2_b32 v14, v4, v5 offset1:1
	v_add_u32_e32 v4, 0x18c8, v11
	ds_write2_b32 v4, v6, v7 offset1:1
	v_lshl_add_u64 v[4:5], v[12:13], 0, v[0:1]
	v_mov_b64_e32 v[4:5], v[64:65]
	v_mov_b64_e32 v[6:7], v[66:67]
	v_add_u32_e32 v0, 0x1ce0, v11
	s_waitcnt vmcnt(0)
	ds_write2_b32 v0, v4, v5 offset1:1
	v_add_u32_e32 v0, 0x1ce8, v11
	ds_write2_b32 v0, v6, v7 offset1:1
	v_mul_u32_u24_e32 v0, 0x420, v3
	v_lshlrev_b32_e32 v4, 2, v9
	s_waitcnt lgkmcnt(0)
	v_or_b32_e32 v11, s4, v9
	v_add3_u32 v9, s30, v0, v4
	ds_read2_b32 v[12:13], v9 offset0:198 offset1:206
	ds_read2_b32 v[14:15], v9 offset0:231 offset1:239
	ds_read2_b32 v[16:17], v9 offset0:132 offset1:140
	ds_read2_b32 v[18:19], v9 offset0:165 offset1:173
	ds_read2_b32 v[20:21], v9 offset0:66 offset1:74
	ds_read2_b32 v[22:23], v9 offset0:99 offset1:107
	ds_read2_b32 v[24:25], v9 offset0:33 offset1:41
	ds_read2_b32 v[26:27], v9 offset1:8
	v_mov_b32_e32 v3, v1
	v_lshl_add_u64 v[2:3], s[10:11], 0, v[2:3]
	v_lshlrev_b32_e32 v0, 11, v11
	v_lshl_add_u64 v[28:29], v[2:3], 0, v[0:1]
	v_or_b32_e32 v0, s4, v30
	s_waitcnt lgkmcnt(6)
	v_cvt_pk_bf16_f32 v7, v12, v14
	s_waitcnt lgkmcnt(4)
	v_cvt_pk_bf16_f32 v6, v16, v18
	s_waitcnt lgkmcnt(2)
	v_cvt_pk_bf16_f32 v5, v20, v22
	s_waitcnt lgkmcnt(0)
	v_cvt_pk_bf16_f32 v4, v26, v24
	v_lshlrev_b32_e32 v0, 11, v0
	global_store_dwordx4 v[28:29], v[4:7], off
	s_nop 1
	v_cvt_pk_bf16_f32 v7, v13, v15
	v_cvt_pk_bf16_f32 v6, v17, v19
	v_cvt_pk_bf16_f32 v5, v21, v23
	v_cvt_pk_bf16_f32 v4, v27, v25
	v_lshl_add_u64 v[12:13], v[2:3], 0, v[0:1]
	global_store_dwordx4 v[12:13], v[4:7], off
	ds_read2_b32 v[12:13], v9 offset0:214 offset1:222
	ds_read2_b32 v[14:15], v9 offset0:247 offset1:255
	ds_read2_b32 v[16:17], v9 offset0:148 offset1:156
	ds_read2_b32 v[18:19], v9 offset0:181 offset1:189
	ds_read2_b32 v[20:21], v9 offset0:82 offset1:90
	ds_read2_b32 v[22:23], v9 offset0:115 offset1:123
	ds_read2_b32 v[24:25], v9 offset0:49 offset1:57
	ds_read2_b32 v[26:27], v9 offset0:16 offset1:24
	v_or_b32_e32 v0, s4, v31
	v_lshlrev_b32_e32 v0, 11, v0
	v_lshl_add_u64 v[28:29], v[2:3], 0, v[0:1]
	v_or_b32_e32 v0, s4, v32
	s_waitcnt lgkmcnt(6)
	v_cvt_pk_bf16_f32 v7, v12, v14
	s_waitcnt lgkmcnt(4)
	v_cvt_pk_bf16_f32 v6, v16, v18
	s_waitcnt lgkmcnt(2)
	v_cvt_pk_bf16_f32 v5, v20, v22
	s_waitcnt lgkmcnt(0)
	v_cvt_pk_bf16_f32 v4, v26, v24
	v_lshlrev_b32_e32 v0, 11, v0
	global_store_dwordx4 v[28:29], v[4:7], off
	v_lshl_add_u64 v[2:3], v[2:3], 0, v[0:1]
	s_nop 0
	v_cvt_pk_bf16_f32 v7, v13, v15
	v_cvt_pk_bf16_f32 v6, v17, v19
	v_cvt_pk_bf16_f32 v5, v21, v23
	v_cvt_pk_bf16_f32 v4, v27, v25
	global_store_dwordx4 v[2:3], v[4:7], off
	s_waitcnt lgkmcnt(0)

.LBB0_610:
	s_andn2_b64 vcc, exec, s[10:11]
	s_cbranch_vccnz .LBB0_612
	s_movk_i32 s4, 0xb0
	v_readlane_b32 s10, v250, 57
	v_readlane_b32 s11, v250, 58
	s_load_dwordx2 s[4:5], s[10:11], s4 offset:0x0
	v_readlane_b32 s10, v236, 21
	v_and_b32_e32 v3, 7, v8
	v_lshlrev_b32_e32 v2, 4, v3
	v_lshrrev_b32_e32 v9, 3, v10
	s_waitcnt lgkmcnt(0)
	s_add_u32 s10, s4, s10
	s_addc_u32 s11, s5, 0
	s_lshl_b32 s4, s31, 1
	s_and_b32 s5, s4, 0x1c0
	s_lshl_b32 s4, s31, 5
	s_and_b32 s4, s4, 0x3e0
	v_lshl_or_b32 v0, s4, 2, v2
	v_lshl_add_u64 v[12:13], s[10:11], 0, v[0:1]
	v_or_b32_e32 v0, s5, v9
	v_lshlrev_b32_e32 v0, 12, v0
	v_lshl_add_u64 v[4:5], v[12:13], 0, v[0:1]
	v_mov_b32_e32 v68, 0x8000
	v_mov_b32_e32 v69, 0
	v_lshl_add_u64 v[70:71], v[4:5], 0, v[68:69]
	global_load_dwordx4 v[40:43], v[70:71], off
	v_lshl_add_u64 v[70:71], v[70:71], 0, v[68:69]
	global_load_dwordx4 v[44:47], v[70:71], off
	v_lshl_add_u64 v[70:71], v[70:71], 0, v[68:69]
	global_load_dwordx4 v[48:51], v[70:71], off
	v_lshl_add_u64 v[70:71], v[70:71], 0, v[68:69]
	global_load_dwordx4 v[52:55], v[70:71], off
	v_lshl_add_u64 v[70:71], v[70:71], 0, v[68:69]
	global_load_dwordx4 v[56:59], v[70:71], off
	v_lshl_add_u64 v[70:71], v[70:71], 0, v[68:69]
	global_load_dwordx4 v[60:63], v[70:71], off
	v_lshl_add_u64 v[70:71], v[70:71], 0, v[68:69]
	global_load_dwordx4 v[64:67], v[70:71], off
	global_load_dwordx4 v[4:7], v[4:5], off
	v_mul_u32_u24_e32 v11, 0x84, v9
	v_add3_u32 v11, s30, v2, v11
	v_or_b32_e32 v30, 8, v9
	v_add_u32_e32 v14, 0x420, v11
	v_or_b32_e32 v31, 16, v9
	v_or_b32_e32 v32, 24, v9
	v_readlane_b32 s10, v236, 23
	s_waitcnt vmcnt(0)
	ds_write2_b32 v11, v4, v5 offset1:1
	ds_write2_b32 v11, v6, v7 offset0:2 offset1:3
	v_or_b32_e32 v4, s5, v30
	v_lshlrev_b32_e32 v4, 12, v4
	v_mov_b32_e32 v5, v1
	v_lshl_add_u64 v[4:5], v[12:13], 0, v[4:5]
	v_mov_b64_e32 v[4:5], v[40:41]
	v_mov_b64_e32 v[6:7], v[42:43]
	s_waitcnt vmcnt(0)
	ds_write2_b32 v14, v4, v5 offset1:1
	v_add_u32_e32 v4, 0x428, v11
	ds_write2_b32 v4, v6, v7 offset1:1
	v_or_b32_e32 v4, s5, v31
	v_lshlrev_b32_e32 v4, 12, v4
	v_mov_b32_e32 v5, v1
	v_lshl_add_u64 v[4:5], v[12:13], 0, v[4:5]
	v_mov_b64_e32 v[4:5], v[44:45]
	v_mov_b64_e32 v[6:7], v[46:47]
	v_add_u32_e32 v14, 0x840, v11
	s_waitcnt vmcnt(0)
	ds_write2_b32 v14, v4, v5 offset1:1
	v_add_u32_e32 v4, 0x848, v11
	ds_write2_b32 v4, v6, v7 offset1:1
	v_or_b32_e32 v4, s5, v32
	v_lshlrev_b32_e32 v4, 12, v4
	v_mov_b32_e32 v5, v1
	v_lshl_add_u64 v[4:5], v[12:13], 0, v[4:5]
	v_mov_b64_e32 v[4:5], v[48:49]
	v_mov_b64_e32 v[6:7], v[50:51]
	v_add_u32_e32 v14, 0xc60, v11
	s_lshl_b32 s5, s5, 1
	s_add_u32 s10, s10, s5
	v_readlane_b32 s5, v236, 25
	s_addc_u32 s11, s5, 0
	s_waitcnt vmcnt(0)
	ds_write2_b32 v14, v4, v5 offset1:1
	v_add_u32_e32 v4, 0xc68, v11
	ds_write2_b32 v4, v6, v7 offset1:1
	v_or_b32_e32 v4, 0x20000, v0
	v_mov_b32_e32 v5, v1
	v_lshl_add_u64 v[4:5], v[12:13], 0, v[4:5]
	v_mov_b64_e32 v[4:5], v[52:53]
	v_mov_b64_e32 v[6:7], v[54:55]
	v_add_u32_e32 v14, 0x1080, v11
	s_waitcnt vmcnt(0)
	ds_write2_b32 v14, v4, v5 offset1:1
	v_add_u32_e32 v4, 0x1088, v11
	ds_write2_b32 v4, v6, v7 offset1:1
	v_or_b32_e32 v4, 0x28000, v0
	v_mov_b32_e32 v5, v1
	v_lshl_add_u64 v[4:5], v[12:13], 0, v[4:5]
	v_mov_b64_e32 v[4:5], v[56:57]
	v_mov_b64_e32 v[6:7], v[58:59]
	v_add_u32_e32 v14, 0x14a0, v11
	s_waitcnt vmcnt(0)
	ds_write2_b32 v14, v4, v5 offset1:1
	v_add_u32_e32 v4, 0x14a8, v11
	ds_write2_b32 v4, v6, v7 offset1:1
	v_or_b32_e32 v4, 0x30000, v0
	v_mov_b32_e32 v5, v1
	v_lshl_add_u64 v[4:5], v[12:13], 0, v[4:5]
	v_mov_b64_e32 v[4:5], v[60:61]
	v_mov_b64_e32 v[6:7], v[62:63]
	v_add_u32_e32 v14, 0x18c0, v11
	v_or_b32_e32 v0, 0x38000, v0
	s_waitcnt vmcnt(0)
	ds_write2_b32 v14, v4, v5 offset1:1
	v_add_u32_e32 v4, 0x18c8, v11
	ds_write2_b32 v4, v6, v7 offset1:1
	v_lshl_add_u64 v[4:5], v[12:13], 0, v[0:1]
	v_mov_b64_e32 v[4:5], v[64:65]
	v_mov_b64_e32 v[6:7], v[66:67]
	v_add_u32_e32 v0, 0x1ce0, v11
	s_waitcnt vmcnt(0)
	ds_write2_b32 v0, v4, v5 offset1:1
	v_add_u32_e32 v0, 0x1ce8, v11
	ds_write2_b32 v0, v6, v7 offset1:1
	v_mul_u32_u24_e32 v0, 0x420, v3
	v_lshlrev_b32_e32 v4, 2, v9
	s_waitcnt lgkmcnt(0)
	v_or_b32_e32 v11, s4, v9
	v_add3_u32 v9, s30, v0, v4
	ds_read2_b32 v[12:13], v9 offset0:198 offset1:206
	ds_read2_b32 v[14:15], v9 offset0:231 offset1:239
	ds_read2_b32 v[16:17], v9 offset0:132 offset1:140
	ds_read2_b32 v[18:19], v9 offset0:165 offset1:173
	ds_read2_b32 v[20:21], v9 offset0:66 offset1:74
	ds_read2_b32 v[22:23], v9 offset0:99 offset1:107
	ds_read2_b32 v[24:25], v9 offset0:33 offset1:41
	ds_read2_b32 v[26:27], v9 offset1:8
	v_mov_b32_e32 v3, v1
	v_lshl_add_u64 v[2:3], s[10:11], 0, v[2:3]
	v_lshlrev_b32_e32 v0, 9, v11
	v_lshl_add_u64 v[28:29], v[2:3], 0, v[0:1]
	v_or_b32_e32 v0, s4, v30
	s_waitcnt lgkmcnt(6)
	v_cvt_pk_bf16_f32 v7, v12, v14
	s_waitcnt lgkmcnt(4)
	v_cvt_pk_bf16_f32 v6, v16, v18
	s_waitcnt lgkmcnt(2)
	v_cvt_pk_bf16_f32 v5, v20, v22
	s_waitcnt lgkmcnt(0)
	v_cvt_pk_bf16_f32 v4, v26, v24
	v_lshlrev_b32_e32 v0, 9, v0
	global_store_dwordx4 v[28:29], v[4:7], off
	s_nop 1
	v_cvt_pk_bf16_f32 v7, v13, v15
	v_cvt_pk_bf16_f32 v6, v17, v19
	v_cvt_pk_bf16_f32 v5, v21, v23
	v_cvt_pk_bf16_f32 v4, v27, v25
	v_lshl_add_u64 v[12:13], v[2:3], 0, v[0:1]
	global_store_dwordx4 v[12:13], v[4:7], off
	ds_read2_b32 v[12:13], v9 offset0:214 offset1:222
	ds_read2_b32 v[14:15], v9 offset0:247 offset1:255
	ds_read2_b32 v[16:17], v9 offset0:148 offset1:156
	ds_read2_b32 v[18:19], v9 offset0:181 offset1:189
	ds_read2_b32 v[20:21], v9 offset0:82 offset1:90
	ds_read2_b32 v[22:23], v9 offset0:115 offset1:123
	ds_read2_b32 v[24:25], v9 offset0:49 offset1:57
	ds_read2_b32 v[26:27], v9 offset0:16 offset1:24
	v_or_b32_e32 v0, s4, v31
	v_lshlrev_b32_e32 v0, 9, v0
	v_lshl_add_u64 v[28:29], v[2:3], 0, v[0:1]
	v_or_b32_e32 v0, s4, v32
	s_waitcnt lgkmcnt(6)
	v_cvt_pk_bf16_f32 v7, v12, v14
	s_waitcnt lgkmcnt(4)
	v_cvt_pk_bf16_f32 v6, v16, v18
	s_waitcnt lgkmcnt(2)
	v_cvt_pk_bf16_f32 v5, v20, v22
	s_waitcnt lgkmcnt(0)
	v_cvt_pk_bf16_f32 v4, v26, v24
	v_lshlrev_b32_e32 v0, 9, v0
	global_store_dwordx4 v[28:29], v[4:7], off
	v_lshl_add_u64 v[2:3], v[2:3], 0, v[0:1]
	s_nop 0
	v_cvt_pk_bf16_f32 v7, v13, v15
	v_cvt_pk_bf16_f32 v6, v17, v19
	v_cvt_pk_bf16_f32 v5, v21, v23
	v_cvt_pk_bf16_f32 v4, v27, v25
	global_store_dwordx4 v[2:3], v[4:7], off
	s_waitcnt lgkmcnt(0)

.LBB0_613:
	s_andn2_b64 vcc, exec, s[10:11]
	s_cbranch_vccnz .LBB0_615
	s_movk_i32 s4, 0xa8
	v_readlane_b32 s10, v250, 57
	v_readlane_b32 s11, v250, 58
	s_load_dwordx2 s[4:5], s[10:11], s4 offset:0x0
	s_mul_i32 s10, s52, 0x300000
	v_and_b32_e32 v3, 7, v8
	v_lshlrev_b32_e32 v2, 4, v3
	v_lshrrev_b32_e32 v9, 3, v10
	s_waitcnt lgkmcnt(0)
	s_add_u32 s10, s4, s10
	s_addc_u32 s11, s5, 0
	s_lshl_b32 s4, s31, 1
	s_add_i32 s4, s4, 0x1fd00
	s_and_b32 s5, s4, 0x1ffc0
	s_lshl_b32 s4, s31, 5
	s_and_b32 s4, s4, 0x3e0
	v_lshl_or_b32 v0, s4, 2, v2
	v_lshl_add_u64 v[12:13], s[10:11], 0, v[0:1]
	v_or_b32_e32 v0, s5, v9
	v_lshlrev_b32_e32 v0, 12, v0
	v_lshl_add_u64 v[4:5], v[12:13], 0, v[0:1]
	v_mov_b32_e32 v68, 0x8000
	v_mov_b32_e32 v69, 0
	v_lshl_add_u64 v[70:71], v[4:5], 0, v[68:69]
	global_load_dwordx4 v[40:43], v[70:71], off
	v_lshl_add_u64 v[70:71], v[70:71], 0, v[68:69]
	global_load_dwordx4 v[44:47], v[70:71], off
	v_lshl_add_u64 v[70:71], v[70:71], 0, v[68:69]
	global_load_dwordx4 v[48:51], v[70:71], off
	v_lshl_add_u64 v[70:71], v[70:71], 0, v[68:69]
	global_load_dwordx4 v[52:55], v[70:71], off
	v_lshl_add_u64 v[70:71], v[70:71], 0, v[68:69]
	global_load_dwordx4 v[56:59], v[70:71], off
	v_lshl_add_u64 v[70:71], v[70:71], 0, v[68:69]
	global_load_dwordx4 v[60:63], v[70:71], off
	v_lshl_add_u64 v[70:71], v[70:71], 0, v[68:69]
	global_load_dwordx4 v[64:67], v[70:71], off
	global_load_dwordx4 v[4:7], v[4:5], off
	v_mul_u32_u24_e32 v11, 0x84, v9
	v_add3_u32 v11, s30, v2, v11
	v_or_b32_e32 v30, 8, v9
	v_add_u32_e32 v14, 0x420, v11
	v_or_b32_e32 v31, 16, v9
	v_or_b32_e32 v32, 24, v9
	v_readlane_b32 s10, v236, 27
	s_waitcnt vmcnt(0)
	ds_write2_b32 v11, v4, v5 offset1:1
	ds_write2_b32 v11, v6, v7 offset0:2 offset1:3
	v_or_b32_e32 v4, s5, v30
	v_lshlrev_b32_e32 v4, 12, v4
	v_mov_b32_e32 v5, v1
	v_lshl_add_u64 v[4:5], v[12:13], 0, v[4:5]
	v_mov_b64_e32 v[4:5], v[40:41]
	v_mov_b64_e32 v[6:7], v[42:43]
	s_waitcnt vmcnt(0)
	ds_write2_b32 v14, v4, v5 offset1:1
	v_add_u32_e32 v4, 0x428, v11
	ds_write2_b32 v4, v6, v7 offset1:1
	v_or_b32_e32 v4, s5, v31
	v_lshlrev_b32_e32 v4, 12, v4
	v_mov_b32_e32 v5, v1
	v_lshl_add_u64 v[4:5], v[12:13], 0, v[4:5]
	v_mov_b64_e32 v[4:5], v[44:45]
	v_mov_b64_e32 v[6:7], v[46:47]
	v_add_u32_e32 v14, 0x840, v11
	s_waitcnt vmcnt(0)
	ds_write2_b32 v14, v4, v5 offset1:1
	v_add_u32_e32 v4, 0x848, v11
	ds_write2_b32 v4, v6, v7 offset1:1
	v_or_b32_e32 v4, s5, v32
	v_lshlrev_b32_e32 v4, 12, v4
	v_mov_b32_e32 v5, v1
	v_lshl_add_u64 v[4:5], v[12:13], 0, v[4:5]
	v_mov_b64_e32 v[4:5], v[48:49]
	v_mov_b64_e32 v[6:7], v[50:51]
	v_add_u32_e32 v14, 0xc60, v11
	s_lshl_b32 s5, s5, 1
	s_add_u32 s10, s10, s5
	v_readlane_b32 s5, v236, 28
	s_addc_u32 s11, s5, 0
	s_waitcnt vmcnt(0)
	ds_write2_b32 v14, v4, v5 offset1:1
	v_add_u32_e32 v4, 0xc68, v11
	ds_write2_b32 v4, v6, v7 offset1:1
	v_or_b32_e32 v4, 0x20000, v0
	v_mov_b32_e32 v5, v1
	v_lshl_add_u64 v[4:5], v[12:13], 0, v[4:5]
	v_mov_b64_e32 v[4:5], v[52:53]
	v_mov_b64_e32 v[6:7], v[54:55]
	v_add_u32_e32 v14, 0x1080, v11
	s_waitcnt vmcnt(0)
	ds_write2_b32 v14, v4, v5 offset1:1
	v_add_u32_e32 v4, 0x1088, v11
	ds_write2_b32 v4, v6, v7 offset1:1
	v_or_b32_e32 v4, 0x28000, v0
	v_mov_b32_e32 v5, v1
	v_lshl_add_u64 v[4:5], v[12:13], 0, v[4:5]
	v_mov_b64_e32 v[4:5], v[56:57]
	v_mov_b64_e32 v[6:7], v[58:59]
	v_add_u32_e32 v14, 0x14a0, v11
	s_waitcnt vmcnt(0)
	ds_write2_b32 v14, v4, v5 offset1:1
	v_add_u32_e32 v4, 0x14a8, v11
	ds_write2_b32 v4, v6, v7 offset1:1
	v_or_b32_e32 v4, 0x30000, v0
	v_mov_b32_e32 v5, v1
	v_lshl_add_u64 v[4:5], v[12:13], 0, v[4:5]
	v_mov_b64_e32 v[4:5], v[60:61]
	v_mov_b64_e32 v[6:7], v[62:63]
	v_add_u32_e32 v14, 0x18c0, v11
	v_or_b32_e32 v0, 0x38000, v0
	s_waitcnt vmcnt(0)
	ds_write2_b32 v14, v4, v5 offset1:1
	v_add_u32_e32 v4, 0x18c8, v11
	ds_write2_b32 v4, v6, v7 offset1:1
	v_lshl_add_u64 v[4:5], v[12:13], 0, v[0:1]
	v_mov_b64_e32 v[4:5], v[64:65]
	v_mov_b64_e32 v[6:7], v[66:67]
	v_add_u32_e32 v0, 0x1ce0, v11
	s_waitcnt vmcnt(0)
	ds_write2_b32 v0, v4, v5 offset1:1
	v_add_u32_e32 v0, 0x1ce8, v11
	ds_write2_b32 v0, v6, v7 offset1:1
	v_mul_u32_u24_e32 v0, 0x420, v3
	v_lshlrev_b32_e32 v4, 2, v9
	s_waitcnt lgkmcnt(0)
	v_or_b32_e32 v11, s4, v9
	v_add3_u32 v9, s30, v0, v4
	ds_read2_b32 v[12:13], v9 offset0:198 offset1:206
	ds_read2_b32 v[14:15], v9 offset0:231 offset1:239
	ds_read2_b32 v[16:17], v9 offset0:132 offset1:140
	ds_read2_b32 v[18:19], v9 offset0:165 offset1:173
	ds_read2_b32 v[20:21], v9 offset0:66 offset1:74
	ds_read2_b32 v[22:23], v9 offset0:99 offset1:107
	ds_read2_b32 v[24:25], v9 offset0:33 offset1:41
	ds_read2_b32 v[26:27], v9 offset1:8
	v_mov_b32_e32 v3, v1
	v_mul_u32_u24_e32 v0, 0x300, v11
	v_lshl_add_u64 v[2:3], s[10:11], 0, v[2:3]
	v_lshlrev_b32_e32 v0, 1, v0
	v_lshl_add_u64 v[28:29], v[2:3], 0, v[0:1]
	v_or_b32_e32 v0, s4, v30
	v_mul_u32_u24_e32 v0, 0x300, v0
	s_waitcnt lgkmcnt(6)
	v_cvt_pk_bf16_f32 v7, v12, v14
	s_waitcnt lgkmcnt(4)
	v_cvt_pk_bf16_f32 v6, v16, v18
	s_waitcnt lgkmcnt(2)
	v_cvt_pk_bf16_f32 v5, v20, v22
	s_waitcnt lgkmcnt(0)
	v_cvt_pk_bf16_f32 v4, v26, v24
	v_lshlrev_b32_e32 v0, 1, v0
	global_store_dwordx4 v[28:29], v[4:7], off
	s_nop 1
	v_cvt_pk_bf16_f32 v7, v13, v15
	v_cvt_pk_bf16_f32 v6, v17, v19
	v_cvt_pk_bf16_f32 v5, v21, v23
	v_cvt_pk_bf16_f32 v4, v27, v25
	v_lshl_add_u64 v[12:13], v[2:3], 0, v[0:1]
	global_store_dwordx4 v[12:13], v[4:7], off
	v_or_b32_e32 v0, s4, v31
	ds_read2_b32 v[12:13], v9 offset0:214 offset1:222
	ds_read2_b32 v[14:15], v9 offset0:247 offset1:255
	ds_read2_b32 v[16:17], v9 offset0:148 offset1:156
	ds_read2_b32 v[18:19], v9 offset0:181 offset1:189
	ds_read2_b32 v[20:21], v9 offset0:82 offset1:90
	ds_read2_b32 v[22:23], v9 offset0:115 offset1:123
	ds_read2_b32 v[24:25], v9 offset0:16 offset1:24
	ds_read2_b32 v[26:27], v9 offset0:49 offset1:57
	v_mul_u32_u24_e32 v0, 0x300, v0
	v_lshlrev_b32_e32 v0, 1, v0
	v_lshl_add_u64 v[28:29], v[2:3], 0, v[0:1]
	v_or_b32_e32 v0, s4, v32
	v_mul_u32_u24_e32 v0, 0x300, v0
	s_waitcnt lgkmcnt(6)
	v_cvt_pk_bf16_f32 v7, v12, v14
	s_waitcnt lgkmcnt(4)
	v_cvt_pk_bf16_f32 v6, v16, v18
	s_waitcnt lgkmcnt(2)
	v_cvt_pk_bf16_f32 v5, v20, v22
	s_waitcnt lgkmcnt(0)
	v_cvt_pk_bf16_f32 v4, v24, v26
	v_lshlrev_b32_e32 v0, 1, v0
	global_store_dwordx4 v[28:29], v[4:7], off
	v_lshl_add_u64 v[2:3], v[2:3], 0, v[0:1]
	s_nop 0
	v_cvt_pk_bf16_f32 v7, v13, v15
	v_cvt_pk_bf16_f32 v6, v17, v19
	v_cvt_pk_bf16_f32 v5, v21, v23
	v_cvt_pk_bf16_f32 v4, v25, v27
	global_store_dwordx4 v[2:3], v[4:7], off
	s_waitcnt lgkmcnt(0)

.LBB0_633:
	s_or_b64 exec, exec, s[26:27]
	v_add_u32_e32 v6, 0x1ce0, v14
	s_waitcnt vmcnt(0)
	ds_write2_b32 v6, v2, v3 offset1:1
	v_add_u32_e32 v2, 0x1ce8, v14
	ds_write2_b32 v2, v4, v5 offset1:1
	v_mov_b32_e32 v2, s30
	s_movk_i32 s5, 0x420
	s_ashr_i32 s11, s10, 31
	v_mad_u32_u24 v5, v0, s5, v2
	s_lshl_b64 s[10:11], s[10:11], 1
	v_readlane_b32 s5, v236, 30
	s_waitcnt lgkmcnt(0)
	s_add_u32 s10, s5, s10
	v_readlane_b32 s5, v236, 31
	s_addc_u32 s11, s5, s11
	v_lshlrev_b32_e32 v0, 4, v0
	v_or_b32_e32 v4, s4, v13
	s_movk_i32 s5, 0x400
	v_lshl_add_u64 v[2:3], s[10:11], 0, v[0:1]
	v_cmp_gt_i32_e32 vcc, s5, v4
	v_lshl_add_u32 v0, v13, 2, v5
	s_and_saveexec_b64 s[10:11], vcc
	s_cbranch_execz .LBB0_635
	ds_read2_b32 v[6:7], v0 offset0:198 offset1:231
	ds_read2_b32 v[14:15], v0 offset1:33
	v_mul_lo_u32 v4, v4, s70
	v_ashrrev_i32_e32 v5, 31, v4
	v_lshl_add_u64 v[4:5], v[4:5], 1, v[2:3]
	s_waitcnt lgkmcnt(1)
	v_cvt_pk_bf16_f32 v9, v6, v7
	ds_read2_b32 v[6:7], v0 offset0:132 offset1:165
	s_waitcnt lgkmcnt(0)
	v_cvt_pk_bf16_f32 v8, v6, v7
	ds_read2_b32 v[6:7], v0 offset0:66 offset1:99
	s_waitcnt lgkmcnt(0)
	v_cvt_pk_bf16_f32 v7, v6, v7
	v_cvt_pk_bf16_f32 v6, v14, v15
	global_store_dwordx4 v[4:5], v[6:9], off

.Lpe1_next:
	s_addk_i32 s91, 0x80
	s_cmpk_lt_i32 s91, 0xa80
	s_cbranch_scc1 .Lpe1_loop
	s_waitcnt vmcnt(0) lgkmcnt(0)
	v_mov_b32_e32 v2, v204
	v_mov_b32_e32 v4, v205
	v_mov_b32_e32 v15, v206
	v_mov_b32_e32 v17, v207
	v_mov_b32_e32 v40, v208
	v_mov_b32_e32 v41, v209
	v_mov_b32_e32 v42, v210
	v_mov_b32_e32 v43, v211
	v_mov_b32_e32 v44, v212
	v_mov_b32_e32 v45, v213
	v_mov_b32_e32 v46, v214
	v_mov_b32_e32 v47, v215
	v_mov_b32_e32 v48, v216
	v_mov_b32_e32 v49, v217
	v_mov_b32_e32 v50, v218
	v_mov_b32_e32 v51, v219
	v_mov_b32_e32 v52, v220
	v_mov_b32_e32 v53, v221
	v_mov_b32_e32 v54, v222
	v_mov_b32_e32 v55, v223
	v_mov_b32_e32 v56, v224
	v_mov_b32_e32 v57, v225
	v_mov_b32_e32 v58, v226
	v_mov_b32_e32 v59, v227
	v_mov_b32_e32 v60, v228
	v_mov_b32_e32 v61, v229
	v_mov_b32_e32 v62, v230
	v_mov_b32_e32 v63, v231
	v_mov_b32_e32 v64, v232
	v_mov_b32_e32 v65, v233
	v_mov_b32_e32 v66, v234
	v_mov_b32_e32 v67, v235
	v_readlane_b32 s0, v237, 0
	v_readlane_b32 s1, v237, 1
	v_readlane_b32 s2, v237, 2
	v_readlane_b32 s3, v237, 3
	v_readlane_b32 s4, v237, 4
	v_readlane_b32 s5, v237, 5
	v_readlane_b32 s6, v237, 6
	v_readlane_b32 s7, v237, 7
	v_readlane_b32 s8, v237, 8
	v_readlane_b32 s9, v237, 9
	v_readlane_b32 s10, v237, 10
	v_readlane_b32 s11, v237, 11
	v_readlane_b32 s12, v237, 12
	v_readlane_b32 s13, v237, 13
	v_readlane_b32 s14, v237, 14
	v_readlane_b32 s15, v237, 15
	v_readlane_b32 s16, v237, 16
	v_readlane_b32 s17, v237, 17
	v_readlane_b32 s18, v237, 18
	v_readlane_b32 s19, v237, 19
	v_readlane_b32 s20, v237, 20
	v_readlane_b32 s21, v237, 21
	v_readlane_b32 s22, v237, 22
	v_readlane_b32 s23, v237, 23
	v_readlane_b32 s24, v237, 24
	v_readlane_b32 s25, v237, 25
	v_readlane_b32 s26, v237, 26
	v_readlane_b32 s27, v237, 27
	v_readlane_b32 s28, v237, 28
	v_readlane_b32 s29, v237, 29
	v_readlane_b32 s30, v237, 30
	v_readlane_b32 s31, v237, 31
	v_readlane_b32 s32, v237, 32
	v_readlane_b32 s33, v237, 33
	v_readlane_b32 s34, v237, 34
	v_readlane_b32 s35, v237, 35
	v_readlane_b32 s36, v237, 36
	v_readlane_b32 s37, v237, 37
	v_readlane_b32 s38, v237, 38
	v_readlane_b32 s39, v237, 39
	v_readlane_b32 s40, v237, 40
	v_readlane_b32 s41, v237, 41
	v_readlane_b32 s42, v237, 42
	v_readlane_b32 s43, v237, 43
	v_readlane_b32 s44, v237, 44
	v_readlane_b32 s45, v237, 45
	v_readlane_b32 s46, v237, 46
	v_readlane_b32 s47, v237, 47
	v_readlane_b32 s48, v237, 48
	v_readlane_b32 s49, v237, 49
	v_readlane_b32 s50, v237, 50
	v_readlane_b32 s51, v237, 51
	v_readlane_b32 s52, v237, 52
	v_readlane_b32 s53, v237, 53
	v_readlane_b32 s54, v237, 54
	v_readlane_b32 s55, v237, 55
	v_readlane_b32 s56, v237, 56
	v_readlane_b32 s57, v237, 57
	v_readlane_b32 s58, v237, 58
	v_readlane_b32 s59, v237, 59
	v_readlane_b32 s60, v237, 60
	v_readlane_b32 s61, v237, 61
	v_readlane_b32 s62, v237, 62
	v_readlane_b32 s63, v237, 63
	v_readlane_b32 s64, v238, 0
	v_readlane_b32 s65, v238, 1
	v_readlane_b32 s66, v238, 2
	v_readlane_b32 s67, v238, 3
	v_readlane_b32 s68, v238, 4
	v_readlane_b32 s69, v238, 5
	v_readlane_b32 s70, v238, 6
	v_readlane_b32 s71, v238, 7
	v_readlane_b32 s72, v238, 8
	v_readlane_b32 s73, v238, 9
	v_readlane_b32 s74, v238, 10
	v_readlane_b32 s75, v238, 11
	v_readlane_b32 s76, v238, 12
	v_readlane_b32 s77, v238, 13
	v_readlane_b32 s78, v238, 14
	v_readlane_b32 s79, v238, 15
	v_readlane_b32 s80, v238, 16
	v_readlane_b32 s81, v238, 17
	v_readlane_b32 s82, v238, 18
	v_readlane_b32 s83, v238, 19
	v_readlane_b32 s84, v238, 20
	v_readlane_b32 s85, v238, 21
	v_readlane_b32 s86, v238, 22
	v_readlane_b32 s87, v238, 23
	v_readlane_b32 s88, v238, 24
	v_readlane_b32 s89, v238, 25
	v_readlane_b32 s90, v238, 26
	v_readlane_b32 s91, v238, 27
	v_readlane_b32 s92, v238, 28
	v_readlane_b32 s93, v238, 29
	v_readlane_b32 s94, v238, 30
	v_readlane_b32 s95, v238, 31
	v_readlane_b32 s96, v238, 32
	v_readlane_b32 s97, v238, 33
	v_readlane_b32 s98, v238, 34
	v_readlane_b32 s99, v238, 35
	s_nop 3
.Lpe1_done:
.LBB0_241:
	s_getreg_b32 s6, hwreg(HW_REG_XCC_ID, 0, 4)
	s_waitcnt vmcnt(0)
	s_barrier
	s_mov_b64 s[4:5], exec
	v_readlane_b32 s8, v250, 5
	v_readlane_b32 s9, v250, 6
	s_and_b64 s[8:9], s[4:5], s[8:9]
	s_mov_b64 exec, s[8:9]
	s_cbranch_execz .LBB0_293
	v_readlane_b32 s7, v250, 38
	s_waitcnt vmcnt(0) expcnt(0) lgkmcnt(0)
	s_and_b32 s48, s6, 15
	v_mov_b32_e32 v0, s7
	ds_read_b32 v3, v0
	v_readlane_b32 s7, v250, 39
	s_waitcnt lgkmcnt(0)
	v_cmp_ne_u32_e32 vcc, 0, v3
	v_mov_b32_e32 v0, s7
	ds_read_b32 v2, v0
	s_cbranch_vccnz .LBB0_257
	s_add_u32 s6, s66, 0x104600
	s_addc_u32 s7, s67, 0
	s_add_u32 s8, s66, 0x104800
	s_addc_u32 s9, s67, 0
	s_add_u32 s10, s66, 0x104900
	s_addc_u32 s11, s67, 0
	s_add_u32 s12, s66, 0x104a00
	s_addc_u32 s13, s67, 0
	s_add_u32 s14, s66, 0x104b00
	s_addc_u32 s15, s67, 0
	s_add_u32 s16, s66, 0x104c00
	s_addc_u32 s17, s67, 0
	s_add_u32 s18, s66, 0x104d00
	s_addc_u32 s19, s67, 0
	s_add_u32 s20, s66, 0x104e00
	s_addc_u32 s21, s67, 0
	s_add_u32 s22, s66, 0x104f00
	s_addc_u32 s23, s67, 0
	s_add_u32 s24, s66, 0x105000
	s_addc_u32 s25, s67, 0
	s_add_u32 s26, s66, 0x105100
	s_addc_u32 s27, s67, 0
	s_add_u32 s28, s66, 0x105200
	s_addc_u32 s29, s67, 0
	s_add_u32 s30, s66, 0x105300
	s_addc_u32 s31, s67, 0
	s_add_u32 s34, s66, 0x105400
	s_addc_u32 s35, s67, 0
	s_add_u32 s36, s66, 0x105500
	s_addc_u32 s37, s67, 0
	s_add_u32 s38, s66, 0x105600
	s_addc_u32 s39, s67, 0
	s_add_u32 s40, s66, 0x105700
	s_addc_u32 s41, s67, 0
	s_mov_b32 s49, 1
	s_branch .LBB0_245

.LBB0_557:
	s_or_b64 exec, exec, s[10:11]
	v_mov_b32_e32 v0, s71
	s_waitcnt lgkmcnt(0)
	s_barrier
	ds_read_b32 v0, v0
	s_movk_i32 s4, 0x7bf
	s_mov_b64 s[10:11], -1
	s_waitcnt lgkmcnt(0)
	v_cmp_lt_i32_e32 vcc, s4, v0
	v_readfirstlane_b32 s91, v0
	s_cbranch_vccnz .LBB0_552
	s_cmpk_gt_i32 s91, 0xbf
	s_cbranch_scc0 .LBB0_790
	s_cmpk_gt_u32 s91, 0x1bf
	s_cbranch_scc0 .LBB0_656
	s_cmpk_gt_u32 s91, 0x7bf
	s_cbranch_scc0 .LBB0_643
	s_branch .LBB0_642
